# rowop kind2 next-layer prep path: 12 serialized MOD/norm-weight x4 loads hoisted to block start (renamed regs, counted waits)
# speedup vs baseline: 1.0158x; 1.0043x over previous
.LBB0_28:
	s_movk_i32 s0, 0x4000
	v_cmp_gt_i32_e32 vcc, s0, v104
	s_or_b64 s[0:1], s[6:7], vcc
	s_and_saveexec_b64 s[8:9], s[0:1]
	s_cbranch_execz .LBB0_27
	s_movk_i32 s0, 0x4000
	v_cmp_gt_i32_e32 vcc, s0, v104
	v_min_i32_e32 v0, 0x4000, v104
	v_ashrrev_i32_e32 v1, 31, v104
	v_readlane_b32 s0, v253, 42
	v_ashrrev_i32_e32 v172, 13, v0
	v_add_u32_e32 v0, 0xffffc000, v104
	v_cndmask_b32_e32 v105, 0, v1, vcc
	v_mov_b32_e32 v2, s0
	v_mov_b32_e32 v3, s89
	v_readlane_b32 s0, v255, 17
	v_cndmask_b32_e32 v0, v0, v104, vcc
	v_mov_b32_e32 v1, v105
	v_cndmask_b32_e32 v3, v2, v3, vcc
	v_mov_b32_e32 v2, s0
	v_mov_b32_e32 v4, s88
	v_cndmask_b32_e32 v2, v2, v4, vcc
	v_lshlrev_b64 v[0:1], 12, v[0:1]
	v_lshl_add_u64 v[120:121], v[2:3], 0, v[0:1]
	v_add_u32_e32 v0, s10, v172
	v_mul_hi_i32_i24_e32 v33, 0x6000, v0
	v_mul_i32_i24_e32 v32, 0x6000, v0
	v_lshl_add_u64 v[0:1], v[120:121], 0, v[192:193]
	s_movk_i32 s12, 0x1000
	v_add_co_u32_e32 v2, vcc, s12, v0
	s_movk_i32 s13, 0x2000
	s_nop 0
	v_addc_co_u32_e32 v3, vcc, 0, v1, vcc
	v_add_co_u32_e32 v4, vcc, s13, v0
	global_load_dwordx4 v[92:95], v[0:1], off nt
	global_load_dwordx4 v[88:91], v[0:1], off offset:1024 nt
	global_load_dwordx4 v[84:87], v[0:1], off offset:2048 nt
	global_load_dwordx4 v[80:83], v[0:1], off offset:3072 nt
	v_addc_co_u32_e32 v5, vcc, 0, v1, vcc
	v_add_co_u32_e32 v0, vcc, s73, v0
	global_load_dwordx4 v[76:79], v[4:5], off offset:-4096 nt
	global_load_dwordx4 v[72:75], v[2:3], off offset:1024 nt
	global_load_dwordx4 v[68:71], v[2:3], off offset:2048 nt
	global_load_dwordx4 v[64:67], v[2:3], off offset:3072 nt
	global_load_dwordx4 v[28:31], v[4:5], off nt
	global_load_dwordx4 v[24:27], v[4:5], off offset:1024 nt
	global_load_dwordx4 v[20:23], v[4:5], off offset:2048 nt
	global_load_dwordx4 v[16:19], v[4:5], off offset:3072 nt
	v_addc_co_u32_e32 v1, vcc, 0, v1, vcc
	global_load_dwordx4 v[12:15], v[0:1], off nt
	global_load_dwordx4 v[8:11], v[0:1], off offset:1024 nt
	global_load_dwordx4 v[4:7], v[0:1], off offset:2048 nt
	s_nop 0
	global_load_dwordx4 v[0:3], v[0:1], off offset:3072 nt
	v_add_u32_e32 v34, 1, v104
	v_ashrrev_i32_e32 v35, 31, v34
	v_lshlrev_b64 v[116:117], 11, v[34:35]
	v_add_u32_e32 v34, 2, v104
	v_ashrrev_i32_e32 v35, 31, v34
	v_lshlrev_b64 v[114:115], 11, v[34:35]
	v_add_u32_e32 v34, 3, v104
	v_ashrrev_i32_e32 v35, 31, v34
	v_cmp_lt_i32_e32 vcc, v211, v210
	v_lshlrev_b64 v[112:113], 11, v[34:35]
	v_lshl_add_u64 v[32:33], s[90:91], 0, v[32:33]
	v_cndmask_b32_e32 v34, v209, v211, vcc
	v_cmp_lt_i32_e32 vcc, v212, v210
	v_lshlrev_b32_e32 v107, 2, v34
	v_lshl_add_u64 v[36:37], v[32:33], 0, v[192:193]
	v_cndmask_b32_e32 v34, v209, v212, vcc
	v_cmp_lt_i32_e32 vcc, v206, v210
	v_lshlrev_b32_e32 v109, 2, v34
	s_mov_b64 s[0:1], 0x345d000
	v_cndmask_b32_e32 v34, v209, v206, vcc
	v_cmp_lt_i32_e32 vcc, v213, v210
	v_lshlrev_b32_e32 v111, 2, v34
	v_lshl_add_u64 v[62:63], v[36:37], 0, s[0:1]
	v_cndmask_b32_e32 v34, v209, v213, vcc
	v_cmp_lt_i32_e32 vcc, v216, v210
	v_lshlrev_b32_e32 v169, 2, v34
	s_mov_b32 s0, 0x345d000
	v_cndmask_b32_e32 v34, v209, v216, vcc
	v_cmp_lt_i32_e32 vcc, v217, v210
	v_lshlrev_b32_e32 v170, 2, v34
	v_lshlrev_b64 v[118:119], 11, v[104:105]
	v_cndmask_b32_e32 v34, v209, v217, vcc
	v_add_co_u32_e32 v36, vcc, s0, v36
	v_lshl_add_u64 v[60:61], v[96:97], 0, v[118:119]
	s_nop 0
	v_addc_co_u32_e32 v37, vcc, 0, v37, vcc
	v_lshlrev_b32_e32 v171, 2, v34
	global_load_dwordx4 v[32:35], v[98:99], off
	v_lshl_add_u64 v[140:141], v[96:97], 0, v[116:117]
	global_load_dwordx4 v[36:39], v[36:37], off
	s_nop 0
	global_load_dwordx4 v[40:43], v[98:99], off offset:1024
	global_load_dwordx4 v[44:47], v[62:63], off offset:1024
	global_load_dwordx4 v[48:51], v[98:99], off offset:2048
	global_load_dwordx4 v[52:55], v[62:63], off offset:2048
	s_mov_b32 s0, 0x358637bd
	s_mov_b32 s16, 0x3a800000
	s_mov_b32 s14, 0x800000
	v_lshl_add_u64 v[134:135], v[96:97], 0, v[114:115]
	v_lshl_add_u64 v[124:125], v[96:97], 0, v[112:113]
	s_waitcnt vmcnt(21)
	v_mov_b32_e32 v138, v92
	s_waitcnt vmcnt(17)
	v_mov_b32_e32 v136, v76
	s_waitcnt vmcnt(16)
	v_mov_b32_e32 v142, v72
	v_mov_b32_e32 v143, v74
	v_mov_b32_e32 v74, v73
	v_mov_b32_e32 v137, v78
	s_waitcnt vmcnt(12)
	v_mov_b32_e32 v72, v24
	v_mov_b32_e32 v73, v26
	v_mov_b32_e32 v26, v25
	v_mov_b32_e32 v24, v68
	v_mov_b32_e32 v25, v70
	v_mov_b32_e32 v70, v69
	s_waitcnt vmcnt(7)
	v_mov_b32_e32 v68, v4
	v_mov_b32_e32 v69, v6
	v_mov_b32_e32 v6, v5
	global_load_dwordx4 v[56:59], v[98:99], off offset:3072
	global_load_dwordx2 v[4:5], v[60:61], off offset:1536
	global_load_dwordx2 v[180:181], v[60:61], off offset:1024
	global_load_dwordx2 v[182:183], v[60:61], off offset:512
	global_load_dwordx2 v[184:185], v[60:61], off
	global_load_dwordx2 v[186:187], v[140:141], off offset:1536
	global_load_dwordx2 v[188:189], v[140:141], off offset:1024
	global_load_dwordx2 v[190:191], v[140:141], off offset:512
	global_load_dwordx2 v[224:225], v[140:141], off
	global_load_dwordx2 v[232:233], v[134:135], off offset:1536
	global_load_dwordx2 v[234:235], v[134:135], off offset:1024
	global_load_dwordx2 v[236:237], v[134:135], off offset:512
	global_load_dwordx2 v[238:239], v[134:135], off
	global_load_dwordx2 v[240:241], v[124:125], off offset:1536
	global_load_dwordx2 v[242:243], v[124:125], off offset:1024
	global_load_dwordx2 v[248:249], v[124:125], off offset:512
	global_load_dwordx2 v[250:251], v[124:125], off
	v_mov_b32_e32 v78, v77
	v_mov_b32_e32 v144, v84
	v_mov_b32_e32 v145, v86
	v_mov_b32_e32 v86, v85
	v_mov_b32_e32 v84, v20
	v_mov_b32_e32 v85, v22
	v_mov_b32_e32 v22, v21
	v_mov_b32_e32 v139, v94
	v_mov_b32_e32 v94, v93
	s_waitcnt vmcnt(22)
	v_mov_b32_e32 v130, v32
	v_mov_b32_e32 v131, v34
	s_waitcnt vmcnt(21)
	v_mov_b32_e32 v122, v36
	s_waitcnt vmcnt(19)
	v_mov_b32_e32 v76, v44
	v_mov_b32_e32 v77, v46
	v_mov_b32_e32 v46, v45
	v_mov_b32_e32 v44, v8
	v_mov_b32_e32 v45, v10
	v_mov_b32_e32 v10, v9
	s_waitcnt vmcnt(17)
	v_mov_b32_e32 v8, v52
	v_mov_b32_e32 v9, v54
	v_mov_b32_e32 v54, v53
	v_mov_b32_e32 v123, v38
	v_mov_b32_e32 v38, v37
	v_mov_b32_e32 v36, v28
	v_mov_b32_e32 v37, v30
	v_mov_b32_e32 v30, v29
	v_mov_b32_e32 v28, v12
	v_mov_b32_e32 v29, v14
	v_mov_b32_e32 v14, v13
	v_mov_b32_e32 v12, v88
	v_mov_b32_e32 v13, v90
	v_mov_b32_e32 v90, v89
	v_mov_b32_e32 v34, v33
	v_mov_b32_e32 v32, v80
	v_mov_b32_e32 v33, v82
	v_mov_b32_e32 v82, v81
	s_waitcnt vmcnt(15)
	v_and_b32_e32 v21, 0xffff0000, v5
	v_and_b32_e32 v20, 0xffff0000, v4
	v_lshlrev_b32_e32 v52, 16, v4
	v_lshlrev_b32_e32 v53, 16, v5
	v_mov_b32_e32 v93, v52
	v_mov_b32_e32 v127, v53
	v_mov_b32_e32 v89, v21
	s_waitcnt vmcnt(14)
	v_mov_b32_e32 v4, v180
	v_mov_b32_e32 v5, v181
	v_and_b32_e32 v146, 0xffff0000, v4
	v_and_b32_e32 v147, 0xffff0000, v5
	v_lshlrev_b32_e32 v148, 16, v4
	v_lshlrev_b32_e32 v149, 16, v5
	v_mov_b32_e32 v4, v146
	v_mov_b32_e32 v5, v20
	v_pk_mul_f32 v[4:5], v[4:5], v[4:5]
	v_mov_b32_e32 v92, v148
	v_mov_b32_e32 v126, v149
	v_pk_fma_f32 v[4:5], v[92:93], v[92:93], v[4:5]
	v_mov_b32_e32 v88, v147
	v_pk_fma_f32 v[4:5], v[126:127], v[126:127], v[4:5]
	s_nop 0
	v_pk_fma_f32 v[88:89], v[88:89], v[88:89], v[4:5]
	s_waitcnt vmcnt(13)
	v_mov_b32_e32 v4, v182
	v_mov_b32_e32 v5, v183
	v_and_b32_e32 v151, 0xffff0000, v5
	v_and_b32_e32 v150, 0xffff0000, v4
	v_lshlrev_b32_e32 v152, 16, v4
	v_lshlrev_b32_e32 v153, 16, v5
	v_mov_b32_e32 v127, v152
	v_mov_b32_e32 v129, v153
	v_mov_b32_e32 v61, v151
	s_waitcnt vmcnt(12)
	v_mov_b32_e32 v4, v184
	v_mov_b32_e32 v5, v185
	v_and_b32_e32 v92, 0xffff0000, v4
	v_and_b32_e32 v93, 0xffff0000, v5
	v_lshlrev_b32_e32 v154, 16, v4
	v_lshlrev_b32_e32 v155, 16, v5
	v_mov_b32_e32 v4, v92
	v_mov_b32_e32 v5, v150
	v_pk_mul_f32 v[4:5], v[4:5], v[4:5]
	v_mov_b32_e32 v126, v154
	v_mov_b32_e32 v128, v155
	v_pk_fma_f32 v[4:5], v[126:127], v[126:127], v[4:5]
	v_mov_b32_e32 v60, v93
	v_pk_fma_f32 v[4:5], v[128:129], v[128:129], v[4:5]
	v_mov_b32_e32 v128, v40
	v_mov_b32_e32 v129, v42
	v_mov_b32_e32 v42, v41
	v_pk_fma_f32 v[156:157], v[60:61], v[60:61], v[4:5]
	global_load_dwordx4 v[60:63], v[62:63], off offset:3072
	v_mov_b32_e32 v126, v48
	v_mov_b32_e32 v127, v50
	v_mov_b32_e32 v50, v49
	v_mov_b32_e32 v4, v56
	v_mov_b32_e32 v5, v58
	v_mov_b32_e32 v58, v57
	s_waitcnt vmcnt(12)
	v_mov_b32_e32 v40, v186
	v_mov_b32_e32 v41, v187
	v_and_b32_e32 v159, 0xffff0000, v41
	v_and_b32_e32 v158, 0xffff0000, v40
	v_lshlrev_b32_e32 v160, 16, v40
	v_lshlrev_b32_e32 v161, 16, v41
	s_waitcnt vmcnt(0)
	v_mov_b32_e32 v132, v60
	v_mov_b32_e32 v133, v62
	v_mov_b32_e32 v62, v61
	v_mov_b32_e32 v61, v160
	v_mov_b32_e32 v81, v161
	v_mov_b32_e32 v57, v159
	s_waitcnt vmcnt(0)
	v_mov_b32_e32 v40, v188
	v_mov_b32_e32 v41, v189
	v_and_b32_e32 v48, 0xffff0000, v40
	v_and_b32_e32 v49, 0xffff0000, v41
	v_lshlrev_b32_e32 v162, 16, v40
	v_lshlrev_b32_e32 v163, 16, v41
	v_mov_b32_e32 v40, v48
	v_mov_b32_e32 v41, v158
	v_pk_mul_f32 v[40:41], v[40:41], v[40:41]
	v_mov_b32_e32 v60, v162
	v_mov_b32_e32 v80, v163
	v_pk_fma_f32 v[40:41], v[60:61], v[60:61], v[40:41]
	v_mov_b32_e32 v56, v49
	v_pk_fma_f32 v[40:41], v[80:81], v[80:81], v[40:41]
	s_nop 0
	v_pk_fma_f32 v[40:41], v[56:57], v[56:57], v[40:41]
	s_waitcnt vmcnt(0)
	v_mov_b32_e32 v56, v190
	v_mov_b32_e32 v57, v191
	v_and_b32_e32 v165, 0xffff0000, v57
	v_and_b32_e32 v164, 0xffff0000, v56
	v_lshlrev_b32_e32 v166, 16, v56
	v_lshlrev_b32_e32 v167, 16, v57
	v_mov_b32_e32 v81, v166
	v_mov_b32_e32 v141, v167
	v_mov_b32_e32 v61, v165
	s_waitcnt vmcnt(0)
	v_mov_b32_e32 v56, v224
	v_mov_b32_e32 v57, v225
	v_and_b32_e32 v174, 0xffff0000, v56
	v_and_b32_e32 v175, 0xffff0000, v57
	v_lshlrev_b32_e32 v176, 16, v56
	v_lshlrev_b32_e32 v177, 16, v57
	v_mov_b32_e32 v56, v174
	v_mov_b32_e32 v57, v164
	v_pk_mul_f32 v[56:57], v[56:57], v[56:57]
	v_mov_b32_e32 v80, v176
	v_mov_b32_e32 v140, v177
	v_pk_fma_f32 v[56:57], v[80:81], v[80:81], v[56:57]
	v_mov_b32_e32 v60, v175
	v_pk_fma_f32 v[56:57], v[140:141], v[140:141], v[56:57]
	v_mov_b64_e32 v[140:141], s[0:1]
	v_pk_fma_f32 v[56:57], v[60:61], v[60:61], v[56:57]
	v_mov_b32_e32 v61, v156
	v_mov_b32_e32 v60, v56
	v_mov_b32_e32 v156, v57
	v_pk_add_f32 v[56:57], v[60:61], v[156:157]
	v_mov_b32_e32 v60, v40
	v_mov_b32_e32 v61, v88
	v_pk_add_f32 v[56:57], v[56:57], v[60:61]
	v_mov_b32_e32 v88, v41
	v_pk_add_f32 v[40:41], v[56:57], v[88:89]
	s_nop 0
	s_nop 1
	v_add_f32_dpp v41, v41, v41 quad_perm:[1,0,3,2] row_mask:0xf bank_mask:0xf
	v_add_f32_dpp v40, v40, v40 quad_perm:[1,0,3,2] row_mask:0xf bank_mask:0xf
	s_nop 0
	v_add_f32_dpp v41, v41, v41 quad_perm:[2,3,0,1] row_mask:0xf bank_mask:0xf
	v_add_f32_dpp v40, v40, v40 quad_perm:[2,3,0,1] row_mask:0xf bank_mask:0xf
	s_nop 0
	v_add_f32_dpp v41, v41, v41 row_half_mirror row_mask:0xf bank_mask:0xf
	v_add_f32_dpp v40, v40, v40 row_half_mirror row_mask:0xf bank_mask:0xf
	s_nop 0
	v_add_f32_dpp v41, v41, v41 row_mirror row_mask:0xf bank_mask:0xf
	v_add_f32_dpp v40, v40, v40 row_mirror row_mask:0xf bank_mask:0xf
	s_nop 0
	v_mov_b32_e32 v57, v41
	v_mov_b32_e32 v56, v40
	s_nop 0
	v_permlane16_swap_b32_e32 v41, v57
	v_permlane16_swap_b32_e32 v40, v56
	s_nop 0
	v_add_f32_e32 v41, v41, v57
	v_add_f32_e32 v40, v40, v56
	s_nop 0
	v_mov_b32_e32 v57, v41
	v_mov_b32_e32 v56, v40
	s_nop 0
	v_permlane32_swap_b32_e32 v41, v57
	v_permlane32_swap_b32_e32 v40, v56
	s_nop 0
	v_add_f32_e32 v41, v41, v57
	v_add_f32_e32 v40, v40, v56
	s_nop 0
	s_nop 0
	v_pk_fma_f32 v[156:157], v[40:41], s[16:17], v[140:141] op_sel_hi:[1,0,0]
	s_nop 0
	v_mul_f32_e32 v40, 0x4b800000, v157
	v_cmp_gt_f32_e64 s[0:1], s14, v157
	v_cmp_gt_f32_e32 vcc, s14, v156
	s_nop 0
	v_cndmask_b32_e64 v40, v157, v40, s[0:1]
	v_rsq_f32_e32 v40, v40
	s_nop 0
	v_mul_f32_e32 v41, 0x45800000, v40
	v_cndmask_b32_e64 v178, v40, v41, s[0:1]
	v_pk_mul_f32 v[40:41], v[178:179], v[154:155] op_sel_hi:[0,1]
	v_pk_mul_f32 v[40:41], v[40:41], v[130:131]
	v_pk_mul_f32 v[56:57], v[178:179], v[92:93] op_sel_hi:[0,1]
	v_pk_fma_f32 v[92:93], v[40:41], v[122:123], v[138:139]
	v_pk_mul_f32 v[40:41], v[178:179], v[152:153] op_sel_hi:[0,1]
	v_pk_mul_f32 v[56:57], v[56:57], v[34:35]
	v_pk_mul_f32 v[40:41], v[40:41], v[128:129]
	v_pk_fma_f32 v[88:89], v[56:57], v[38:39], v[94:95]
	v_pk_mul_f32 v[56:57], v[178:179], v[150:151] op_sel_hi:[0,1]
	v_pk_fma_f32 v[80:81], v[40:41], v[76:77], v[12:13]
	v_pk_mul_f32 v[12:13], v[178:179], v[148:149] op_sel_hi:[0,1]
	v_pk_mul_f32 v[56:57], v[56:57], v[42:43]
	v_pk_mul_f32 v[12:13], v[12:13], v[126:127]
	v_pk_fma_f32 v[60:61], v[56:57], v[46:47], v[90:91]
	v_pk_fma_f32 v[56:57], v[12:13], v[8:9], v[144:145]
	v_pk_mul_f32 v[12:13], v[178:179], v[52:53] op_sel_hi:[0,1]
	v_pk_mul_f32 v[20:21], v[178:179], v[20:21] op_sel_hi:[0,1]
	v_pk_mul_f32 v[12:13], v[12:13], v[4:5]
	v_pk_mul_f32 v[20:21], v[20:21], v[58:59]
	v_pk_fma_f32 v[32:33], v[12:13], v[132:133], v[32:33]
	v_pk_fma_f32 v[12:13], v[20:21], v[62:63], v[82:83]
	v_mul_f32_e32 v20, 0x4b800000, v156
	v_cndmask_b32_e32 v20, v156, v20, vcc
	v_rsq_f32_e32 v20, v20
	v_pk_mul_f32 v[40:41], v[178:179], v[146:147] op_sel_hi:[0,1]
	v_pk_mul_f32 v[40:41], v[40:41], v[50:51]
	v_mul_f32_e32 v21, 0x45800000, v20
	v_cndmask_b32_e32 v20, v20, v21, vcc
	v_pk_mul_f32 v[48:49], v[20:21], v[48:49] op_sel_hi:[0,1]
	v_pk_mul_f32 v[48:49], v[48:49], v[50:51]
	v_pk_mul_f32 v[82:83], v[20:21], v[174:175] op_sel_hi:[0,1]
	v_pk_fma_f32 v[48:49], v[48:49], v[54:55], v[70:71]
	v_mov_b32_e32 v70, v64
	v_mov_b32_e32 v71, v66
	v_mov_b32_e32 v66, v65
	v_pk_mul_f32 v[82:83], v[82:83], v[34:35]
	v_pk_mul_f32 v[52:53], v[20:21], v[176:177] op_sel_hi:[0,1]
	v_pk_fma_f32 v[82:83], v[82:83], v[38:39], v[78:79]
	v_pk_mul_f32 v[78:79], v[20:21], v[164:165] op_sel_hi:[0,1]
	v_pk_mul_f32 v[90:91], v[78:79], v[42:43]
	v_pk_mul_f32 v[52:53], v[52:53], v[130:131]
	v_pk_fma_f32 v[74:75], v[90:91], v[46:47], v[74:75]
	v_pk_fma_f32 v[40:41], v[40:41], v[54:55], v[86:87]
	v_pk_fma_f32 v[86:87], v[52:53], v[122:123], v[136:137]
	v_pk_mul_f32 v[52:53], v[20:21], v[166:167] op_sel_hi:[0,1]
	v_pk_mul_f32 v[52:53], v[52:53], v[128:129]
	s_waitcnt vmcnt(0)
	v_mov_b32_e32 v64, v232
	v_mov_b32_e32 v65, v233
	v_and_b32_e32 v91, 0xffff0000, v65
	v_and_b32_e32 v90, 0xffff0000, v64
	v_lshlrev_b32_e32 v94, 16, v64
	v_lshlrev_b32_e32 v95, 16, v65
	v_pk_fma_f32 v[78:79], v[52:53], v[76:77], v[142:143]
	v_pk_mul_f32 v[52:53], v[20:21], v[162:163] op_sel_hi:[0,1]
	v_pk_mul_f32 v[52:53], v[52:53], v[126:127]
	v_mov_b32_e32 v143, v95
	v_pk_fma_f32 v[52:53], v[52:53], v[8:9], v[24:25]
	v_pk_mul_f32 v[24:25], v[20:21], v[160:161] op_sel_hi:[0,1]
	v_pk_mul_f32 v[24:25], v[24:25], v[4:5]
	v_pk_mul_f32 v[20:21], v[20:21], v[158:159] op_sel_hi:[0,1]
	v_pk_fma_f32 v[24:25], v[24:25], v[132:133], v[70:71]
	v_mov_b32_e32 v71, v94
	v_pk_mul_f32 v[20:21], v[20:21], v[58:59]
	s_waitcnt vmcnt(0)
	v_mov_b32_e32 v64, v234
	v_mov_b32_e32 v65, v235
	v_and_b32_e32 v136, 0xffff0000, v64
	v_and_b32_e32 v137, 0xffff0000, v65
	v_lshlrev_b32_e32 v138, 16, v64
	v_lshlrev_b32_e32 v139, 16, v65
	v_mov_b32_e32 v64, v136
	v_mov_b32_e32 v65, v90
	v_pk_mul_f32 v[64:65], v[64:65], v[64:65]
	v_mov_b32_e32 v70, v138
	v_pk_fma_f32 v[64:65], v[70:71], v[70:71], v[64:65]
	v_mov_b32_e32 v142, v139
	v_pk_fma_f32 v[20:21], v[20:21], v[62:63], v[66:67]
	v_mov_b32_e32 v66, v137
	v_mov_b32_e32 v67, v91
	v_pk_fma_f32 v[64:65], v[142:143], v[142:143], v[64:65]
	s_waitcnt vmcnt(0)
	v_mov_b32_e32 v70, v236
	v_mov_b32_e32 v71, v237
	v_lshlrev_b32_e32 v142, 16, v70
	v_pk_fma_f32 v[66:67], v[66:67], v[66:67], v[64:65]
	v_and_b32_e32 v64, 0xffff0000, v70
	s_waitcnt vmcnt(0)
	v_mov_b32_e32 v134, v238
	v_mov_b32_e32 v135, v239
	v_and_b32_e32 v70, 0xffff0000, v134
	v_and_b32_e32 v65, 0xffff0000, v71
	v_lshlrev_b32_e32 v143, 16, v71
	v_and_b32_e32 v71, 0xffff0000, v135
	v_lshlrev_b32_e32 v144, 16, v134
	v_lshlrev_b32_e32 v145, 16, v135
	v_mov_b32_e32 v134, v70
	v_mov_b32_e32 v135, v64
	v_pk_mul_f32 v[134:135], v[134:135], v[134:135]
	v_mov_b32_e32 v148, v144
	v_mov_b32_e32 v149, v142
	v_mov_b32_e32 v150, v145
	v_mov_b32_e32 v151, v143
	v_pk_fma_f32 v[134:135], v[148:149], v[148:149], v[134:135]
	v_mov_b32_e32 v146, v71
	v_mov_b32_e32 v147, v65
	v_pk_fma_f32 v[134:135], v[150:151], v[150:151], v[134:135]
	s_nop 0
	v_pk_fma_f32 v[154:155], v[146:147], v[146:147], v[134:135]
	v_mov_b32_e32 v134, v16
	v_mov_b32_e32 v135, v18
	v_mov_b32_e32 v18, v17
	s_waitcnt vmcnt(0)
	v_mov_b32_e32 v16, v240
	v_mov_b32_e32 v17, v241
	v_and_b32_e32 v147, 0xffff0000, v17
	v_and_b32_e32 v146, 0xffff0000, v16
	v_lshlrev_b32_e32 v148, 16, v16
	v_lshlrev_b32_e32 v149, 16, v17
	v_mov_b32_e32 v159, v148
	v_mov_b32_e32 v161, v149
	v_mov_b32_e32 v157, v147
	s_waitcnt vmcnt(0)
	v_mov_b32_e32 v16, v242
	v_mov_b32_e32 v17, v243
	v_and_b32_e32 v150, 0xffff0000, v16
	v_and_b32_e32 v151, 0xffff0000, v17
	v_lshlrev_b32_e32 v152, 16, v16
	v_lshlrev_b32_e32 v153, 16, v17
	v_mov_b32_e32 v16, v150
	v_mov_b32_e32 v17, v146
	v_pk_mul_f32 v[16:17], v[16:17], v[16:17]
	v_mov_b32_e32 v158, v152
	v_pk_fma_f32 v[16:17], v[158:159], v[158:159], v[16:17]
	v_mov_b32_e32 v160, v153
	v_mov_b32_e32 v156, v151
	v_pk_fma_f32 v[16:17], v[160:161], v[160:161], v[16:17]
	s_waitcnt vmcnt(0)
	v_mov_b32_e32 v158, v248
	v_mov_b32_e32 v159, v249
	v_mov_b32_e32 v124, v250
	v_mov_b32_e32 v125, v251
	v_and_b32_e32 v160, 0xffff0000, v124
	v_pk_fma_f32 v[16:17], v[156:157], v[156:157], v[16:17]
	v_and_b32_e32 v156, 0xffff0000, v158
	v_lshlrev_b32_e32 v158, 16, v158
	v_lshlrev_b32_e32 v124, 16, v124
	v_mov_b32_e32 v162, v160
	v_mov_b32_e32 v163, v156
	v_and_b32_e32 v157, 0xffff0000, v159
	v_lshlrev_b32_e32 v159, 16, v159
	v_and_b32_e32 v161, 0xffff0000, v125
	v_lshlrev_b32_e32 v125, 16, v125
	v_pk_mul_f32 v[162:163], v[162:163], v[162:163]
	v_mov_b32_e32 v166, v124
	v_mov_b32_e32 v167, v158
	v_mov_b32_e32 v174, v125
	v_mov_b32_e32 v175, v159
	v_pk_fma_f32 v[162:163], v[166:167], v[166:167], v[162:163]
	v_mov_b32_e32 v164, v161
	v_mov_b32_e32 v165, v157
	v_pk_fma_f32 v[162:163], v[174:175], v[174:175], v[162:163]
	s_nop 0
	v_pk_fma_f32 v[162:163], v[164:165], v[164:165], v[162:163]
	v_mov_b32_e32 v165, v154
	v_mov_b32_e32 v164, v162
	v_mov_b32_e32 v154, v163
	v_pk_add_f32 v[154:155], v[164:165], v[154:155]
	v_mov_b32_e32 v162, v16
	v_mov_b32_e32 v163, v66
	v_pk_add_f32 v[154:155], v[154:155], v[162:163]
	v_mov_b32_e32 v66, v17
	v_pk_add_f32 v[16:17], v[154:155], v[66:67]
	s_nop 0
	s_nop 1
	v_add_f32_dpp v17, v17, v17 quad_perm:[1,0,3,2] row_mask:0xf bank_mask:0xf
	v_add_f32_dpp v16, v16, v16 quad_perm:[1,0,3,2] row_mask:0xf bank_mask:0xf
	s_nop 0
	v_add_f32_dpp v17, v17, v17 quad_perm:[2,3,0,1] row_mask:0xf bank_mask:0xf
	v_add_f32_dpp v16, v16, v16 quad_perm:[2,3,0,1] row_mask:0xf bank_mask:0xf
	s_nop 0
	v_add_f32_dpp v17, v17, v17 row_half_mirror row_mask:0xf bank_mask:0xf
	v_add_f32_dpp v16, v16, v16 row_half_mirror row_mask:0xf bank_mask:0xf
	s_nop 0
	v_add_f32_dpp v17, v17, v17 row_mirror row_mask:0xf bank_mask:0xf
	v_add_f32_dpp v16, v16, v16 row_mirror row_mask:0xf bank_mask:0xf
	s_nop 0
	v_mov_b32_e32 v67, v17
	v_mov_b32_e32 v66, v16
	s_nop 0
	v_permlane16_swap_b32_e32 v17, v67
	v_permlane16_swap_b32_e32 v16, v66
	s_nop 0
	v_add_f32_e32 v17, v17, v67
	v_add_f32_e32 v16, v16, v66
	s_nop 0
	v_mov_b32_e32 v67, v17
	v_mov_b32_e32 v66, v16
	s_nop 0
	v_permlane32_swap_b32_e32 v17, v67
	v_permlane32_swap_b32_e32 v16, v66
	s_nop 0
	v_add_f32_e32 v17, v17, v67
	v_add_f32_e32 v16, v16, v66
	s_nop 0
	s_nop 0
	v_pk_fma_f32 v[140:141], v[16:17], s[16:17], v[140:141] op_sel_hi:[1,0,0]
	s_nop 0
	v_mul_f32_e32 v16, 0x4b800000, v141
	v_cmp_gt_f32_e64 s[0:1], s14, v141
	v_cmp_gt_f32_e32 vcc, s14, v140
	s_nop 0
	v_cndmask_b32_e64 v16, v141, v16, s[0:1]
	v_rsq_f32_e32 v16, v16
	s_nop 0
	v_mul_f32_e32 v17, 0x45800000, v16
	v_cndmask_b32_e64 v16, v16, v17, s[0:1]
	v_pk_mul_f32 v[66:67], v[16:17], v[144:145] op_sel_hi:[0,1]
	v_pk_mul_f32 v[70:71], v[16:17], v[70:71] op_sel_hi:[0,1]
	v_pk_mul_f32 v[66:67], v[130:131], v[66:67]
	v_pk_mul_f32 v[144:145], v[34:35], v[70:71]
	v_pk_fma_f32 v[70:71], v[122:123], v[66:67], v[36:37]
	v_pk_fma_f32 v[66:67], v[144:145], v[38:39], v[30:31]
	v_pk_mul_f32 v[30:31], v[16:17], v[142:143] op_sel_hi:[0,1]
	v_pk_mul_f32 v[36:37], v[16:17], v[64:65] op_sel_hi:[0,1]
	v_pk_mul_f32 v[30:31], v[30:31], v[128:129]
	v_pk_mul_f32 v[36:37], v[36:37], v[42:43]
	v_pk_fma_f32 v[64:65], v[30:31], v[76:77], v[72:73]
	v_pk_fma_f32 v[36:37], v[36:37], v[46:47], v[26:27]
	v_pk_mul_f32 v[26:27], v[16:17], v[138:139] op_sel_hi:[0,1]
	v_pk_mul_f32 v[30:31], v[16:17], v[136:137] op_sel_hi:[0,1]
	v_pk_mul_f32 v[26:27], v[26:27], v[126:127]
	v_pk_mul_f32 v[72:73], v[30:31], v[50:51]
	v_pk_fma_f32 v[30:31], v[26:27], v[8:9], v[84:85]
	v_pk_fma_f32 v[26:27], v[72:73], v[54:55], v[22:23]
	v_pk_mul_f32 v[22:23], v[16:17], v[94:95] op_sel_hi:[0,1]
	v_pk_mul_f32 v[16:17], v[16:17], v[90:91] op_sel_hi:[0,1]
	v_pk_mul_f32 v[16:17], v[16:17], v[58:59]
	v_pk_mul_f32 v[22:23], v[22:23], v[4:5]
	v_pk_fma_f32 v[16:17], v[16:17], v[62:63], v[18:19]
	v_mul_f32_e32 v18, 0x4b800000, v140
	v_cndmask_b32_e32 v18, v140, v18, vcc
	v_rsq_f32_e32 v18, v18
	v_pk_fma_f32 v[22:23], v[22:23], v[132:133], v[134:135]
	v_mul_f32_e32 v19, 0x45800000, v18
	v_cndmask_b32_e32 v18, v18, v19, vcc
	v_pk_mul_f32 v[72:73], v[18:19], v[124:125] op_sel_hi:[0,1]
	v_pk_mul_f32 v[84:85], v[18:19], v[160:161] op_sel_hi:[0,1]
	v_pk_mul_f32 v[72:73], v[130:131], v[72:73]
	v_pk_mul_f32 v[34:35], v[34:35], v[84:85]
	v_pk_fma_f32 v[84:85], v[122:123], v[72:73], v[28:29]
	v_pk_fma_f32 v[72:73], v[38:39], v[34:35], v[14:15]
	v_pk_mul_f32 v[14:15], v[18:19], v[158:159] op_sel_hi:[0,1]
	v_pk_mul_f32 v[28:29], v[18:19], v[156:157] op_sel_hi:[0,1]
	v_pk_mul_f32 v[14:15], v[128:129], v[14:15]
	v_pk_mul_f32 v[28:29], v[42:43], v[28:29]
	v_pk_fma_f32 v[42:43], v[14:15], v[76:77], v[44:45]
	v_pk_fma_f32 v[38:39], v[28:29], v[46:47], v[10:11]
	v_pk_mul_f32 v[10:11], v[18:19], v[152:153] op_sel_hi:[0,1]
	v_pk_mul_f32 v[14:15], v[18:19], v[150:151] op_sel_hi:[0,1]
	v_pk_mul_f32 v[10:11], v[10:11], v[126:127]
	v_pk_mul_f32 v[14:15], v[14:15], v[50:51]
	v_pk_fma_f32 v[34:35], v[10:11], v[8:9], v[68:69]
	v_pk_fma_f32 v[28:29], v[14:15], v[54:55], v[6:7]
	v_pk_mul_f32 v[6:7], v[18:19], v[148:149] op_sel_hi:[0,1]
	v_mov_b32_e32 v8, v0
	v_mov_b32_e32 v9, v2
	v_mov_b32_e32 v2, v1
	v_lshlrev_b64 v[0:1], 12, v[104:105]
	v_pk_mul_f32 v[4:5], v[6:7], v[4:5]
	v_pk_mul_f32 v[6:7], v[18:19], v[146:147] op_sel_hi:[0,1]
	v_lshl_add_u64 v[0:1], s[88:89], 0, v[0:1]
	v_pk_mul_f32 v[6:7], v[6:7], v[58:59]
	v_cndmask_b32_e64 v1, v121, v1, s[2:3]
	v_cndmask_b32_e64 v0, v120, v0, s[2:3]
	v_pk_fma_f32 v[14:15], v[4:5], v[132:133], v[8:9]
	v_pk_fma_f32 v[18:19], v[6:7], v[62:63], v[2:3]
	v_lshl_add_u64 v[4:5], v[0:1], 0, v[192:193]
	v_mov_b32_e32 v0, v92
	v_mov_b32_e32 v1, v88
	v_mov_b32_e32 v2, v93
	v_mov_b32_e32 v3, v89
	global_store_dwordx4 v[4:5], v[0:3], off nt
	v_add_co_u32_e32 v6, vcc, s12, v4
	s_nop 0
	v_mov_b32_e32 v0, v80
	v_mov_b32_e32 v1, v60
	v_mov_b32_e32 v2, v81
	v_mov_b32_e32 v3, v61
	global_store_dwordx4 v[4:5], v[0:3], off offset:1024 nt
	v_addc_co_u32_e32 v7, vcc, 0, v5, vcc
	s_nop 0
	v_mov_b32_e32 v0, v56
	v_mov_b32_e32 v1, v40
	v_mov_b32_e32 v2, v57
	v_mov_b32_e32 v3, v41
	global_store_dwordx4 v[4:5], v[0:3], off offset:2048 nt
	v_add_co_u32_e32 v8, vcc, s13, v4
	s_nop 0
	v_mov_b32_e32 v0, v32
	v_mov_b32_e32 v1, v12
	v_mov_b32_e32 v2, v33
	v_mov_b32_e32 v3, v13
	global_store_dwordx4 v[4:5], v[0:3], off offset:3072 nt
	v_addc_co_u32_e32 v9, vcc, 0, v5, vcc
	s_nop 0
	v_mov_b32_e32 v0, v86
	v_mov_b32_e32 v1, v82
	v_mov_b32_e32 v2, v87
	v_mov_b32_e32 v3, v83
	global_store_dwordx4 v[8:9], v[0:3], off offset:-4096 nt
	v_add_co_u32_e32 v4, vcc, s73, v4
	s_nop 0
	v_mov_b32_e32 v0, v78
	v_mov_b32_e32 v1, v74
	v_mov_b32_e32 v2, v79
	v_mov_b32_e32 v3, v75
	global_store_dwordx4 v[6:7], v[0:3], off offset:1024 nt
	v_addc_co_u32_e32 v5, vcc, 0, v5, vcc
	s_nop 0
	v_mov_b32_e32 v0, v52
	v_mov_b32_e32 v1, v48
	v_mov_b32_e32 v2, v53
	v_mov_b32_e32 v3, v49
	global_store_dwordx4 v[6:7], v[0:3], off offset:2048 nt
	s_andn2_b64 vcc, exec, s[4:5]
	s_nop 0
	v_mov_b32_e32 v0, v24
	v_mov_b32_e32 v1, v20
	v_mov_b32_e32 v2, v25
	v_mov_b32_e32 v3, v21
	global_store_dwordx4 v[6:7], v[0:3], off offset:3072 nt
	s_nop 1
	v_mov_b32_e32 v0, v70
	v_mov_b32_e32 v1, v66
	v_mov_b32_e32 v2, v71
	v_mov_b32_e32 v3, v67
	global_store_dwordx4 v[8:9], v[0:3], off nt
	s_nop 1
	v_mov_b32_e32 v0, v64
	v_mov_b32_e32 v1, v36
	v_mov_b32_e32 v2, v65
	v_mov_b32_e32 v3, v37
	global_store_dwordx4 v[8:9], v[0:3], off offset:1024 nt
	s_nop 1
	v_mov_b32_e32 v0, v30
	v_mov_b32_e32 v1, v26
	v_mov_b32_e32 v2, v31
	v_mov_b32_e32 v3, v27
	global_store_dwordx4 v[8:9], v[0:3], off offset:2048 nt
	s_nop 1
	v_mov_b32_e32 v0, v22
	v_mov_b32_e32 v1, v16
	v_mov_b32_e32 v2, v23
	v_mov_b32_e32 v3, v17
	global_store_dwordx4 v[8:9], v[0:3], off offset:3072 nt
	s_nop 1
	v_mov_b32_e32 v0, v84
	v_mov_b32_e32 v1, v72
	v_mov_b32_e32 v2, v85
	v_mov_b32_e32 v3, v73
	global_store_dwordx4 v[4:5], v[0:3], off nt
	s_nop 1
	v_mov_b32_e32 v0, v42
	v_mov_b32_e32 v1, v38
	v_mov_b32_e32 v2, v43
	v_mov_b32_e32 v3, v39
	global_store_dwordx4 v[4:5], v[0:3], off offset:1024 nt
	s_nop 1
	v_mov_b32_e32 v0, v34
	v_mov_b32_e32 v1, v28
	v_mov_b32_e32 v2, v35
	v_mov_b32_e32 v3, v29
	global_store_dwordx4 v[4:5], v[0:3], off offset:2048 nt
	s_nop 1
	v_mov_b32_e32 v0, v14
	v_mov_b32_e32 v1, v18
	v_mov_b32_e32 v2, v15
	v_mov_b32_e32 v3, v19
	global_store_dwordx4 v[4:5], v[0:3], off offset:3072 nt
	s_cbranch_vccnz .LBB0_27
	v_mov_b32_e32 v4, v88
	v_add_u32_e32 v94, v172, v168
	v_mul_hi_i32_i24_e32 v95, 0x6000, v94
	v_mul_i32_i24_e32 v120, 0x6000, v94
	v_mov_b32_e32 v122, v120
	v_mov_b32_e32 v123, v95
	v_lshl_add_u64 v[124:125], s[96:97], 0, v[122:123]
	v_lshl_add_u64 v[94:95], v[124:125], 0, v[192:193]
	v_mov_b32_e32 v120, v193
	v_mov_b32_e32 v121, v193
	v_mov_b32_e32 v122, v193
	s_mov_b64 s[98:99], 0x1000
	v_lshl_add_u64 v[126:127], v[124:125], 0, s[98:99]
	v_lshl_add_u64 v[136:137], v[126:127], 0, v[192:193]
	global_load_dwordx4 v[138:141], v[100:101], off
	global_load_dwordx4 v[142:145], v[136:137], off
	global_load_dwordx4 v[146:149], v[94:95], off
	v_mov_b32_e32 v150, v106
	v_mov_b32_e32 v151, v120
	v_lshl_add_u64 v[152:153], v[126:127], 0, v[150:151]
	global_load_dwordx4 v[154:157], v[100:101], off offset:1024
	global_load_dwordx4 v[158:161], v[152:153], off
	global_load_dwordx4 v[162:165], v[94:95], off offset:1024
	v_mov_b32_e32 v150, v108
	v_mov_b32_e32 v151, v121
	v_lshl_add_u64 v[166:167], v[126:127], 0, v[150:151]
	global_load_dwordx4 v[150:153], v[100:101], off offset:2048
	global_load_dwordx4 v[174:177], v[166:167], off
	global_load_dwordx4 v[180:183], v[94:95], off offset:2048
	v_mov_b32_e32 v170, v110
	v_mov_b32_e32 v171, v122
	v_lshl_add_u64 v[184:185], v[126:127], 0, v[170:171]
	global_load_dwordx4 v[186:189], v[100:101], off offset:3072
	global_load_dwordx4 v[232:235], v[184:185], off
	global_load_dwordx4 v[236:239], v[94:95], off offset:3072
	v_mov_b32_e32 v5, v60
	v_mov_b32_e32 v2, v92
	v_mov_b32_e32 v3, v80
	v_pk_mul_f32 v[4:5], v[4:5], v[4:5]
	v_mov_b32_e32 v6, v40
	v_pk_fma_f32 v[2:3], v[2:3], v[2:3], v[4:5]
	v_mov_b32_e32 v4, v93
	v_mov_b32_e32 v5, v81
	v_pk_fma_f32 v[2:3], v[4:5], v[4:5], v[2:3]
	v_mov_b32_e32 v4, v89
	v_mov_b32_e32 v5, v61
	v_mov_b32_e32 v7, v12
	v_pk_fma_f32 v[2:3], v[4:5], v[4:5], v[2:3]
	v_mov_b32_e32 v4, v56
	v_mov_b32_e32 v5, v32
	v_pk_mul_f32 v[6:7], v[6:7], v[6:7]
	v_mov_b32_e32 v8, v82
	v_pk_fma_f32 v[4:5], v[4:5], v[4:5], v[6:7]
	v_mov_b32_e32 v6, v57
	v_mov_b32_e32 v7, v33
	v_pk_fma_f32 v[4:5], v[6:7], v[6:7], v[4:5]
	v_mov_b32_e32 v6, v41
	v_mov_b32_e32 v7, v13
	v_mov_b32_e32 v9, v74
	v_pk_fma_f32 v[4:5], v[6:7], v[6:7], v[4:5]
	v_mov_b32_e32 v6, v86
	v_mov_b32_e32 v7, v78
	v_pk_mul_f32 v[8:9], v[8:9], v[8:9]
	v_mov_b32_e32 v10, v48
	v_pk_fma_f32 v[6:7], v[6:7], v[6:7], v[8:9]
	v_mov_b32_e32 v8, v87
	v_mov_b32_e32 v9, v79
	v_pk_fma_f32 v[6:7], v[8:9], v[8:9], v[6:7]
	v_mov_b32_e32 v8, v83
	v_mov_b32_e32 v9, v75
	v_mov_b32_e32 v11, v20
	v_pk_fma_f32 v[6:7], v[8:9], v[8:9], v[6:7]
	v_mov_b32_e32 v8, v52
	v_mov_b32_e32 v9, v24
	v_pk_mul_f32 v[10:11], v[10:11], v[10:11]
	s_mov_b32 s0, 0x358637bd
	v_pk_fma_f32 v[8:9], v[8:9], v[8:9], v[10:11]
	v_mov_b32_e32 v10, v53
	v_mov_b32_e32 v11, v25
	v_pk_fma_f32 v[8:9], v[10:11], v[10:11], v[8:9]
	v_mov_b32_e32 v10, v49
	v_mov_b32_e32 v11, v21
	v_pk_fma_f32 v[8:9], v[10:11], v[10:11], v[8:9]
	v_mov_b32_e32 v10, v6
	v_mov_b32_e32 v11, v2
	v_mov_b32_e32 v2, v7
	v_pk_add_f32 v[2:3], v[10:11], v[2:3]
	v_mov_b32_e32 v6, v8
	v_mov_b32_e32 v7, v4
	v_pk_add_f32 v[2:3], v[2:3], v[6:7]
	v_mov_b32_e32 v4, v9
	v_pk_add_f32 v[2:3], v[2:3], v[4:5]
	s_mov_b32 s14, 0x3a800000
	s_mov_b32 s12, 0x800000
	v_mov_b32_e32 v7, v36
	v_mov_b32_e32 v8, v26
	v_mov_b32_e32 v9, v16
	v_pk_mul_f32 v[8:9], v[8:9], v[8:9]
	v_mov_b32_e32 v10, v72
	v_mov_b32_e32 v11, v38
	v_pk_mul_f32 v[10:11], v[10:11], v[10:11]
	v_mov_b32_e32 v50, v28
	v_mov_b32_e32 v51, v18
	v_pk_mul_f32 v[50:51], v[50:51], v[50:51]
	v_add_u32_e32 v0, v172, v168
	v_mul_hi_i32_i24_e32 v1, 0x6000, v0
	v_mul_i32_i24_e32 v0, 0x6000, v0
	v_lshl_add_u64 v[0:1], s[96:97], 0, v[0:1]
	v_lshl_add_u64 v[62:63], v[0:1], 0, v[192:193]
	v_lshl_add_u64 v[58:59], v[102:103], 0, v[118:119]
	s_nop 0
	s_nop 1
	v_add_f32_dpp v3, v3, v3 quad_perm:[1,0,3,2] row_mask:0xf bank_mask:0xf
	v_add_f32_dpp v2, v2, v2 quad_perm:[1,0,3,2] row_mask:0xf bank_mask:0xf
	s_nop 0
	v_add_f32_dpp v3, v3, v3 quad_perm:[2,3,0,1] row_mask:0xf bank_mask:0xf
	v_add_f32_dpp v2, v2, v2 quad_perm:[2,3,0,1] row_mask:0xf bank_mask:0xf
	s_nop 0
	v_add_f32_dpp v3, v3, v3 row_half_mirror row_mask:0xf bank_mask:0xf
	v_add_f32_dpp v2, v2, v2 row_half_mirror row_mask:0xf bank_mask:0xf
	s_nop 0
	v_add_f32_dpp v3, v3, v3 row_mirror row_mask:0xf bank_mask:0xf
	v_add_f32_dpp v2, v2, v2 row_mirror row_mask:0xf bank_mask:0xf
	s_nop 0
	v_mov_b32_e32 v5, v3
	v_mov_b32_e32 v4, v2
	s_nop 0
	v_permlane16_swap_b32_e32 v3, v5
	v_permlane16_swap_b32_e32 v2, v4
	s_nop 0
	v_add_f32_e32 v3, v3, v5
	v_add_f32_e32 v2, v2, v4
	s_nop 0
	v_mov_b32_e32 v5, v3
	v_mov_b32_e32 v4, v2
	s_nop 0
	v_permlane32_swap_b32_e32 v3, v5
	v_permlane32_swap_b32_e32 v2, v4
	s_nop 0
	v_add_f32_e32 v3, v3, v5
	v_add_f32_e32 v2, v2, v4
	s_nop 0
	v_mov_b64_e32 v[4:5], s[0:1]
	v_pk_fma_f32 v[2:3], v[2:3], s[14:15], v[4:5] op_sel_hi:[1,0,0]
	s_nop 0
	v_mul_f32_e32 v6, 0x4b800000, v3
	v_cmp_gt_f32_e64 s[0:1], s12, v3
	v_cmp_gt_f32_e32 vcc, s12, v2
	s_nop 0
	v_cndmask_b32_e64 v3, v3, v6, s[0:1]
	v_rsq_f32_e32 v3, v3
	s_nop 0
	v_mul_f32_e32 v6, 0x45800000, v3
	v_cndmask_b32_e64 v46, v3, v6, s[0:1]
	v_mul_f32_e32 v3, 0x4b800000, v2
	v_cndmask_b32_e32 v2, v2, v3, vcc
	v_rsq_f32_e32 v2, v2
	v_mov_b32_e32 v6, v66
	v_pk_mul_f32 v[6:7], v[6:7], v[6:7]
	v_pk_mul_f32 v[88:89], v[88:89], v[46:47] op_sel_hi:[1,0]
	v_mul_f32_e32 v3, 0x45800000, v2
	v_cndmask_b32_e32 v44, v2, v3, vcc
	v_mov_b32_e32 v2, v70
	v_mov_b32_e32 v3, v64
	v_pk_fma_f32 v[2:3], v[2:3], v[2:3], v[6:7]
	v_mov_b32_e32 v6, v71
	v_mov_b32_e32 v7, v65
	v_pk_fma_f32 v[2:3], v[6:7], v[6:7], v[2:3]
	v_mov_b32_e32 v6, v67
	v_mov_b32_e32 v7, v37
	v_pk_fma_f32 v[2:3], v[6:7], v[6:7], v[2:3]
	v_mov_b32_e32 v6, v30
	v_mov_b32_e32 v7, v22
	v_pk_fma_f32 v[6:7], v[6:7], v[6:7], v[8:9]
	v_mov_b32_e32 v8, v31
	v_mov_b32_e32 v9, v23
	v_pk_fma_f32 v[6:7], v[8:9], v[8:9], v[6:7]
	v_mov_b32_e32 v8, v27
	v_mov_b32_e32 v9, v17
	v_pk_fma_f32 v[6:7], v[8:9], v[8:9], v[6:7]
	v_mov_b32_e32 v8, v84
	v_mov_b32_e32 v9, v42
	v_pk_fma_f32 v[8:9], v[8:9], v[8:9], v[10:11]
	v_mov_b32_e32 v10, v85
	v_mov_b32_e32 v11, v43
	v_pk_fma_f32 v[8:9], v[10:11], v[10:11], v[8:9]
	v_mov_b32_e32 v10, v73
	v_mov_b32_e32 v11, v39
	v_pk_fma_f32 v[8:9], v[10:11], v[10:11], v[8:9]
	v_mov_b32_e32 v10, v34
	v_mov_b32_e32 v11, v14
	v_pk_fma_f32 v[10:11], v[10:11], v[10:11], v[50:51]
	v_mov_b32_e32 v50, v35
	v_mov_b32_e32 v51, v15
	v_pk_fma_f32 v[10:11], v[50:51], v[50:51], v[10:11]
	v_mov_b32_e32 v50, v29
	v_mov_b32_e32 v51, v19
	v_pk_fma_f32 v[10:11], v[50:51], v[50:51], v[10:11]
	v_mov_b32_e32 v50, v8
	v_mov_b32_e32 v51, v2
	v_mov_b32_e32 v2, v9
	v_pk_add_f32 v[2:3], v[50:51], v[2:3]
	v_mov_b32_e32 v8, v10
	v_mov_b32_e32 v9, v6
	v_pk_add_f32 v[2:3], v[2:3], v[8:9]
	v_mov_b32_e32 v6, v11
	v_pk_add_f32 v[2:3], v[2:3], v[6:7]
	v_mov_b32_e32 v107, v193
	v_mov_b32_e32 v109, v193
	v_mov_b32_e32 v111, v193
	s_nop 0
	s_nop 1
	v_add_f32_dpp v3, v3, v3 quad_perm:[1,0,3,2] row_mask:0xf bank_mask:0xf
	v_add_f32_dpp v2, v2, v2 quad_perm:[1,0,3,2] row_mask:0xf bank_mask:0xf
	s_nop 0
	v_add_f32_dpp v3, v3, v3 quad_perm:[2,3,0,1] row_mask:0xf bank_mask:0xf
	v_add_f32_dpp v2, v2, v2 quad_perm:[2,3,0,1] row_mask:0xf bank_mask:0xf
	s_nop 0
	v_add_f32_dpp v3, v3, v3 row_half_mirror row_mask:0xf bank_mask:0xf
	v_add_f32_dpp v2, v2, v2 row_half_mirror row_mask:0xf bank_mask:0xf
	s_nop 0
	v_add_f32_dpp v3, v3, v3 row_mirror row_mask:0xf bank_mask:0xf
	v_add_f32_dpp v2, v2, v2 row_mirror row_mask:0xf bank_mask:0xf
	s_nop 0
	v_mov_b32_e32 v7, v3
	v_mov_b32_e32 v6, v2
	s_nop 0
	v_permlane16_swap_b32_e32 v3, v7
	v_permlane16_swap_b32_e32 v2, v6
	s_nop 0
	v_add_f32_e32 v3, v3, v7
	v_add_f32_e32 v2, v2, v6
	s_nop 0
	v_mov_b32_e32 v7, v3
	v_mov_b32_e32 v6, v2
	s_nop 0
	v_permlane32_swap_b32_e32 v3, v7
	v_permlane32_swap_b32_e32 v2, v6
	s_nop 0
	v_add_f32_e32 v3, v3, v7
	v_add_f32_e32 v2, v2, v6
	s_nop 0
	s_nop 0
	v_pk_fma_f32 v[2:3], v[2:3], s[14:15], v[4:5] op_sel_hi:[1,0,0]
	s_nop 0
	v_mul_f32_e32 v4, 0x4b800000, v3
	v_cmp_gt_f32_e64 s[0:1], s12, v3
	v_cmp_gt_f32_e32 vcc, s12, v2
	s_nop 0
	v_cndmask_b32_e64 v3, v3, v4, s[0:1]
	v_rsq_f32_e32 v3, v3
	s_nop 0
	v_mul_f32_e32 v4, 0x45800000, v3
	v_cndmask_b32_e64 v54, v3, v4, s[0:1]
	v_mul_f32_e32 v3, 0x4b800000, v2
	v_cndmask_b32_e32 v2, v2, v3, vcc
	v_rsq_f32_e32 v2, v2
	s_mov_b64 s[98:99], 0x1000
	v_lshl_add_u64 v[68:69], v[0:1], 0, s[98:99]
	v_lshl_add_u64 v[4:5], v[68:69], 0, v[192:193]
	v_mul_f32_e32 v3, 0x45800000, v2
	v_cndmask_b32_e32 v50, v2, v3, vcc
	s_nop 0
	v_pk_mul_f32 v[66:67], v[66:67], v[54:55] op_sel_hi:[1,0]
	v_pk_mul_f32 v[36:37], v[36:37], v[54:55] op_sel_hi:[1,0]
	v_pk_mul_f32 v[26:27], v[26:27], v[54:55] op_sel_hi:[1,0]
	s_waitcnt vmcnt(11)
	v_mov_b32_e32 v0, v138
	v_mov_b32_e32 v1, v139
	v_mov_b32_e32 v2, v140
	v_mov_b32_e32 v3, v141
	v_mov_b32_e32 v90, v0
	s_waitcnt vmcnt(10)
	v_mov_b32_e32 v8, v142
	v_mov_b32_e32 v9, v143
	v_mov_b32_e32 v10, v144
	v_mov_b32_e32 v11, v145
	v_mov_b32_e32 v76, v8
	v_mov_b32_e32 v77, v10
	v_mov_b32_e32 v10, v9
	v_pk_mul_f32 v[8:9], v[92:93], v[46:47] op_sel_hi:[1,0]
	v_mov_b32_e32 v91, v2
	v_pk_add_f32 v[76:77], v[76:77], 1.0 op_sel_hi:[1,0]
	v_pk_mul_f32 v[8:9], v[8:9], v[90:91]
	s_waitcnt vmcnt(9)
	v_mov_b32_e32 v4, v146
	v_mov_b32_e32 v5, v147
	v_mov_b32_e32 v6, v148
	v_mov_b32_e32 v7, v149
	v_mov_b32_e32 v92, v4
	v_mov_b32_e32 v93, v6
	v_mov_b32_e32 v2, v1
	v_pk_add_f32 v[10:11], v[10:11], 1.0 op_sel_hi:[1,0]
	v_pk_fma_f32 v[8:9], v[8:9], v[76:77], v[92:93]
	v_pk_mul_f32 v[0:1], v[88:89], v[2:3]
	v_mov_b32_e32 v6, v5
	v_pk_fma_f32 v[0:1], v[0:1], v[10:11], v[6:7]
	v_cvt_pk_bf16_f32 v0, v8, v0
	v_cvt_pk_bf16_f32 v1, v9, v1
	v_pk_mul_f32 v[4:5], v[86:87], v[44:45] op_sel_hi:[1,0]
	v_pk_mul_f32 v[8:9], v[82:83], v[44:45] op_sel_hi:[1,0]
	v_pk_mul_f32 v[4:5], v[4:5], v[90:91]
	v_pk_mul_f32 v[8:9], v[8:9], v[2:3]
	v_pk_fma_f32 v[4:5], v[4:5], v[76:77], v[92:93]
	v_pk_fma_f32 v[8:9], v[8:9], v[10:11], v[6:7]
	v_cvt_pk_bf16_f32 v5, v5, v9
	v_cvt_pk_bf16_f32 v4, v4, v8
	v_pk_mul_f32 v[8:9], v[70:71], v[54:55] op_sel_hi:[1,0]
	v_pk_mul_f32 v[66:67], v[2:3], v[66:67]
	v_pk_mul_f32 v[8:9], v[90:91], v[8:9]
	v_pk_fma_f32 v[66:67], v[66:67], v[10:11], v[6:7]
	v_pk_fma_f32 v[8:9], v[8:9], v[76:77], v[92:93]
	v_pk_mul_f32 v[70:71], v[72:73], v[50:51] op_sel_hi:[1,0]
	v_cvt_pk_bf16_f32 v9, v9, v67
	v_and_b32_sdwa v47, v8, v218 dst_sel:DWORD dst_unused:UNUSED_PAD src0_sel:WORD_1 src1_sel:DWORD
	v_add3_u32 v8, v8, v47, s80
	v_and_b32_sdwa v47, v66, v218 dst_sel:DWORD dst_unused:UNUSED_PAD src0_sel:WORD_1 src1_sel:DWORD
	v_add3_u32 v47, v66, v47, s80
	v_pk_mul_f32 v[66:67], v[84:85], v[50:51] op_sel_hi:[1,0]
	v_pk_mul_f32 v[2:3], v[2:3], v[70:71]
	v_pk_mul_f32 v[66:67], v[90:91], v[66:67]
	v_pk_fma_f32 v[2:3], v[10:11], v[2:3], v[6:7]
	v_pk_fma_f32 v[66:67], v[76:77], v[66:67], v[92:93]
	global_store_dwordx2 v[58:59], v[0:1], off
	v_lshl_add_u64 v[0:1], v[102:103], 0, v[116:117]
	v_and_b32_e32 v47, 0xffff0000, v47
	v_cvt_pk_bf16_f32 v3, v67, v3
	v_cvt_pk_bf16_f32 v2, v66, v2
	global_store_dwordx2 v[0:1], v[4:5], off
	v_lshl_add_u64 v[4:5], v[102:103], 0, v[114:115]
	v_or_b32_sdwa v8, v47, v8 dst_sel:DWORD dst_unused:UNUSED_PAD src0_sel:DWORD src1_sel:WORD_1
	global_store_dwordx2 v[4:5], v[8:9], off
	v_lshl_add_u64 v[8:9], v[102:103], 0, v[112:113]
	global_store_dwordx2 v[8:9], v[2:3], off
	v_lshl_add_u64 v[2:3], v[68:69], 0, v[106:107]
	v_pk_mul_f32 v[10:11], v[80:81], v[46:47] op_sel_hi:[1,0]
	v_pk_mul_f32 v[60:61], v[60:61], v[46:47] op_sel_hi:[1,0]
	s_waitcnt vmcnt(12)
	v_mov_b32_e32 v70, v154
	v_mov_b32_e32 v71, v155
	v_mov_b32_e32 v72, v156
	v_mov_b32_e32 v73, v157
	v_mov_b32_e32 v66, v70
	s_waitcnt vmcnt(11)
	v_mov_b32_e32 v82, v158
	v_mov_b32_e32 v83, v159
	v_mov_b32_e32 v84, v160
	v_mov_b32_e32 v85, v161
	v_mov_b32_e32 v2, v82
	v_mov_b32_e32 v3, v84
	v_mov_b32_e32 v67, v72
	v_pk_add_f32 v[2:3], v[2:3], 1.0 op_sel_hi:[1,0]
	v_mov_b32_e32 v84, v83
	v_pk_mul_f32 v[10:11], v[10:11], v[66:67]
	s_waitcnt vmcnt(10)
	v_mov_b32_e32 v86, v162
	v_mov_b32_e32 v87, v163
	v_mov_b32_e32 v88, v164
	v_mov_b32_e32 v89, v165
	v_mov_b32_e32 v76, v86
	v_mov_b32_e32 v77, v88
	v_mov_b32_e32 v72, v71
	v_pk_add_f32 v[6:7], v[84:85], 1.0 op_sel_hi:[1,0]
	v_pk_fma_f32 v[10:11], v[10:11], v[2:3], v[76:77]
	v_pk_mul_f32 v[60:61], v[60:61], v[72:73]
	v_mov_b32_e32 v88, v87
	v_pk_fma_f32 v[60:61], v[60:61], v[6:7], v[88:89]
	v_and_b32_sdwa v45, v11, v218 dst_sel:DWORD dst_unused:UNUSED_PAD src0_sel:WORD_1 src1_sel:DWORD
	v_cvt_pk_bf16_f32 v10, v10, v60
	v_add3_u32 v11, v11, v45, s80
	v_and_b32_sdwa v45, v61, v218 dst_sel:DWORD dst_unused:UNUSED_PAD src0_sel:WORD_1 src1_sel:DWORD
	v_add3_u32 v45, v61, v45, s80
	v_and_b32_e32 v45, 0xffff0000, v45
	v_or_b32_sdwa v11, v45, v11 dst_sel:DWORD dst_unused:UNUSED_PAD src0_sel:DWORD src1_sel:WORD_1
	global_store_dwordx2 v[58:59], v[10:11], off offset:512
	v_pk_mul_f32 v[10:11], v[78:79], v[44:45] op_sel_hi:[1,0]
	v_pk_mul_f32 v[60:61], v[74:75], v[44:45] op_sel_hi:[1,0]
	v_pk_mul_f32 v[10:11], v[10:11], v[66:67]
	v_pk_mul_f32 v[60:61], v[60:61], v[72:73]
	v_pk_fma_f32 v[10:11], v[10:11], v[2:3], v[76:77]
	v_pk_fma_f32 v[60:61], v[60:61], v[6:7], v[88:89]
	v_cvt_pk_bf16_f32 v11, v11, v61
	v_cvt_pk_bf16_f32 v10, v10, v60
	global_store_dwordx2 v[0:1], v[10:11], off offset:512
	v_pk_mul_f32 v[10:11], v[64:65], v[54:55] op_sel_hi:[1,0]
	v_pk_mul_f32 v[36:37], v[36:37], v[72:73]
	v_pk_mul_f32 v[10:11], v[10:11], v[66:67]
	v_pk_fma_f32 v[36:37], v[36:37], v[6:7], v[88:89]
	v_pk_fma_f32 v[10:11], v[10:11], v[2:3], v[76:77]
	s_nop 0
	v_and_b32_sdwa v45, v11, v218 dst_sel:DWORD dst_unused:UNUSED_PAD src0_sel:WORD_1 src1_sel:DWORD
	v_and_b32_sdwa v47, v10, v218 dst_sel:DWORD dst_unused:UNUSED_PAD src0_sel:WORD_1 src1_sel:DWORD
	v_add3_u32 v10, v10, v47, s80
	v_add3_u32 v11, v11, v45, s80
	v_and_b32_sdwa v45, v37, v218 dst_sel:DWORD dst_unused:UNUSED_PAD src0_sel:WORD_1 src1_sel:DWORD
	v_and_b32_sdwa v47, v36, v218 dst_sel:DWORD dst_unused:UNUSED_PAD src0_sel:WORD_1 src1_sel:DWORD
	v_add3_u32 v37, v37, v45, s80
	v_add3_u32 v36, v36, v47, s80
	v_and_b32_e32 v37, 0xffff0000, v37
	v_and_b32_e32 v36, 0xffff0000, v36
	v_or_b32_sdwa v11, v37, v11 dst_sel:DWORD dst_unused:UNUSED_PAD src0_sel:DWORD src1_sel:WORD_1
	v_or_b32_sdwa v10, v36, v10 dst_sel:DWORD dst_unused:UNUSED_PAD src0_sel:DWORD src1_sel:WORD_1
	global_store_dwordx2 v[4:5], v[10:11], off offset:512
	v_pk_mul_f32 v[10:11], v[42:43], v[50:51] op_sel_hi:[1,0]
	v_pk_mul_f32 v[40:41], v[40:41], v[46:47] op_sel_hi:[1,0]
	v_pk_mul_f32 v[10:11], v[10:11], v[66:67]
	v_pk_mul_f32 v[12:13], v[12:13], v[46:47] op_sel_hi:[1,0]
	v_pk_fma_f32 v[2:3], v[10:11], v[2:3], v[76:77]
	v_pk_mul_f32 v[10:11], v[38:39], v[50:51] op_sel_hi:[1,0]
	s_nop 0
	v_pk_mul_f32 v[10:11], v[10:11], v[72:73]
	s_nop 0
	v_pk_fma_f32 v[6:7], v[10:11], v[6:7], v[88:89]
	v_cvt_pk_bf16_f32 v3, v3, v7
	v_cvt_pk_bf16_f32 v2, v2, v6
	global_store_dwordx2 v[8:9], v[2:3], off offset:512
	v_lshl_add_u64 v[2:3], v[68:69], 0, v[108:109]
	v_pk_mul_f32 v[10:11], v[56:57], v[46:47] op_sel_hi:[1,0]
	s_waitcnt vmcnt(13)
	v_mov_b32_e32 v36, v150
	v_mov_b32_e32 v37, v151
	v_mov_b32_e32 v38, v152
	v_mov_b32_e32 v39, v153
	v_mov_b32_e32 v42, v36
	s_waitcnt vmcnt(12)
	v_mov_b32_e32 v64, v174
	v_mov_b32_e32 v65, v175
	v_mov_b32_e32 v66, v176
	v_mov_b32_e32 v67, v177
	v_mov_b32_e32 v2, v64
	v_mov_b32_e32 v3, v66
	v_mov_b32_e32 v43, v38
	v_pk_add_f32 v[2:3], v[2:3], 1.0 op_sel_hi:[1,0]
	v_mov_b32_e32 v66, v65
	v_pk_mul_f32 v[10:11], v[10:11], v[42:43]
	s_waitcnt vmcnt(11)
	v_mov_b32_e32 v70, v180
	v_mov_b32_e32 v71, v181
	v_mov_b32_e32 v72, v182
	v_mov_b32_e32 v73, v183
	v_mov_b32_e32 v56, v70
	v_mov_b32_e32 v57, v72
	v_mov_b32_e32 v38, v37
	v_pk_add_f32 v[6:7], v[66:67], 1.0 op_sel_hi:[1,0]
	v_pk_fma_f32 v[10:11], v[10:11], v[2:3], v[56:57]
	v_pk_mul_f32 v[36:37], v[40:41], v[38:39]
	v_mov_b32_e32 v72, v71
	v_pk_fma_f32 v[36:37], v[36:37], v[6:7], v[72:73]
	v_cvt_pk_bf16_f32 v11, v11, v37
	v_cvt_pk_bf16_f32 v10, v10, v36
	global_store_dwordx2 v[58:59], v[10:11], off offset:1024
	v_pk_mul_f32 v[10:11], v[52:53], v[44:45] op_sel_hi:[1,0]
	v_pk_mul_f32 v[36:37], v[48:49], v[44:45] op_sel_hi:[1,0]
	v_pk_mul_f32 v[10:11], v[10:11], v[42:43]
	v_pk_mul_f32 v[36:37], v[36:37], v[38:39]
	v_pk_fma_f32 v[10:11], v[10:11], v[2:3], v[56:57]
	v_pk_fma_f32 v[36:37], v[36:37], v[6:7], v[72:73]
	v_cvt_pk_bf16_f32 v11, v11, v37
	v_cvt_pk_bf16_f32 v10, v10, v36
	global_store_dwordx2 v[0:1], v[10:11], off offset:1024
	v_pk_mul_f32 v[10:11], v[30:31], v[54:55] op_sel_hi:[1,0]
	v_pk_mul_f32 v[26:27], v[26:27], v[38:39]
	v_pk_mul_f32 v[10:11], v[10:11], v[42:43]
	v_pk_fma_f32 v[26:27], v[26:27], v[6:7], v[72:73]
	v_pk_fma_f32 v[10:11], v[10:11], v[2:3], v[56:57]
	s_nop 0
	v_cvt_pk_bf16_f32 v11, v11, v27
	v_cvt_pk_bf16_f32 v10, v10, v26
	global_store_dwordx2 v[4:5], v[10:11], off offset:1024
	v_pk_mul_f32 v[10:11], v[34:35], v[50:51] op_sel_hi:[1,0]
	s_nop 0
	v_pk_mul_f32 v[10:11], v[10:11], v[42:43]
	s_nop 0
	v_pk_fma_f32 v[2:3], v[10:11], v[2:3], v[56:57]
	v_pk_mul_f32 v[10:11], v[28:29], v[50:51] op_sel_hi:[1,0]
	s_nop 0
	v_pk_mul_f32 v[10:11], v[10:11], v[38:39]
	s_nop 0
	v_pk_fma_f32 v[6:7], v[10:11], v[6:7], v[72:73]
	v_cvt_pk_bf16_f32 v3, v3, v7
	v_cvt_pk_bf16_f32 v2, v2, v6
	global_store_dwordx2 v[8:9], v[2:3], off offset:1024
	v_lshl_add_u64 v[2:3], v[68:69], 0, v[110:111]
	v_pk_mul_f32 v[10:11], v[32:33], v[46:47] op_sel_hi:[1,0]
	s_waitcnt vmcnt(14)
	v_mov_b32_e32 v26, v186
	v_mov_b32_e32 v27, v187
	v_mov_b32_e32 v28, v188
	v_mov_b32_e32 v29, v189
	v_mov_b32_e32 v30, v26
	s_waitcnt vmcnt(13)
	v_mov_b32_e32 v34, v232
	v_mov_b32_e32 v35, v233
	v_mov_b32_e32 v36, v234
	v_mov_b32_e32 v37, v235
	v_mov_b32_e32 v2, v34
	v_mov_b32_e32 v3, v36
	v_mov_b32_e32 v31, v28
	v_pk_add_f32 v[2:3], v[2:3], 1.0 op_sel_hi:[1,0]
	v_mov_b32_e32 v36, v35
	v_pk_mul_f32 v[10:11], v[10:11], v[30:31]
	s_waitcnt vmcnt(12)
	v_mov_b32_e32 v38, v236
	v_mov_b32_e32 v39, v237
	v_mov_b32_e32 v40, v238
	v_mov_b32_e32 v41, v239
	v_mov_b32_e32 v32, v38
	v_mov_b32_e32 v33, v40
	v_mov_b32_e32 v28, v27
	v_pk_add_f32 v[6:7], v[36:37], 1.0 op_sel_hi:[1,0]
	v_pk_fma_f32 v[10:11], v[10:11], v[2:3], v[32:33]
	v_pk_mul_f32 v[12:13], v[12:13], v[28:29]
	v_mov_b32_e32 v40, v39
	v_pk_fma_f32 v[12:13], v[12:13], v[6:7], v[40:41]
	v_cvt_pk_bf16_f32 v11, v11, v13
	v_cvt_pk_bf16_f32 v10, v10, v12
	global_store_dwordx2 v[58:59], v[10:11], off offset:1536
	v_pk_mul_f32 v[10:11], v[24:25], v[44:45] op_sel_hi:[1,0]
	v_pk_mul_f32 v[12:13], v[20:21], v[44:45] op_sel_hi:[1,0]
	v_pk_mul_f32 v[10:11], v[10:11], v[30:31]
	v_pk_mul_f32 v[12:13], v[12:13], v[28:29]
	v_pk_fma_f32 v[10:11], v[10:11], v[2:3], v[32:33]
	v_pk_fma_f32 v[12:13], v[12:13], v[6:7], v[40:41]
	v_cvt_pk_bf16_f32 v11, v11, v13
	v_cvt_pk_bf16_f32 v10, v10, v12
	global_store_dwordx2 v[0:1], v[10:11], off offset:1536
	v_pk_mul_f32 v[0:1], v[22:23], v[54:55] op_sel_hi:[1,0]
	v_pk_mul_f32 v[10:11], v[16:17], v[54:55] op_sel_hi:[1,0]
	v_pk_mul_f32 v[0:1], v[0:1], v[30:31]
	v_pk_mul_f32 v[10:11], v[10:11], v[28:29]
	v_pk_fma_f32 v[0:1], v[0:1], v[2:3], v[32:33]
	v_pk_fma_f32 v[10:11], v[10:11], v[6:7], v[40:41]
	v_cvt_pk_bf16_f32 v1, v1, v11
	v_cvt_pk_bf16_f32 v0, v0, v10
	global_store_dwordx2 v[4:5], v[0:1], off offset:1536
	v_pk_mul_f32 v[0:1], v[14:15], v[50:51] op_sel_hi:[1,0]
	s_nop 0
	v_pk_mul_f32 v[0:1], v[0:1], v[30:31]
	s_nop 0
	v_pk_fma_f32 v[0:1], v[0:1], v[2:3], v[32:33]
	v_pk_mul_f32 v[2:3], v[18:19], v[50:51] op_sel_hi:[1,0]
	v_and_b32_sdwa v4, v1, v218 dst_sel:DWORD dst_unused:UNUSED_PAD src0_sel:WORD_1 src1_sel:DWORD
	v_pk_mul_f32 v[2:3], v[2:3], v[28:29]
	v_and_b32_sdwa v5, v0, v218 dst_sel:DWORD dst_unused:UNUSED_PAD src0_sel:WORD_1 src1_sel:DWORD
	v_pk_fma_f32 v[2:3], v[2:3], v[6:7], v[40:41]
	v_add3_u32 v0, v0, v5, s80
	v_add3_u32 v1, v1, v4, s80
	v_and_b32_sdwa v4, v3, v218 dst_sel:DWORD dst_unused:UNUSED_PAD src0_sel:WORD_1 src1_sel:DWORD
	v_and_b32_sdwa v5, v2, v218 dst_sel:DWORD dst_unused:UNUSED_PAD src0_sel:WORD_1 src1_sel:DWORD
	v_add3_u32 v3, v3, v4, s80
	v_add3_u32 v2, v2, v5, s80
	v_and_b32_e32 v3, 0xffff0000, v3
	v_and_b32_e32 v2, 0xffff0000, v2
	v_or_b32_sdwa v1, v3, v1 dst_sel:DWORD dst_unused:UNUSED_PAD src0_sel:DWORD src1_sel:WORD_1
	v_or_b32_sdwa v0, v2, v0 dst_sel:DWORD dst_unused:UNUSED_PAD src0_sel:DWORD src1_sel:WORD_1
	global_store_dwordx2 v[8:9], v[0:1], off offset:1536
	s_branch .LBB0_27
